# de-serialized dependent global-load round trips: sample-mLSTM n0 dot + 16-block epilogue (both copies), P6 BC/BW loads, attn_sample PV loop 8 loads in flight
# speedup vs baseline: 1.0126x; 1.0117x over previous
; __device__ __forceinline__ float bf2f(bf16_t h) { return __uint_as_float((unsigned)h << 16); }
; __device__ __forceinline__ void mlstm_sample_unit(const Frame& F, int b, int h) {
;     ...
;     for (int i = tid; i < 1024; i += 512) { const int t = i >> 8, d = i & 255; const bf16_t* row = P + (size_t)(SP + b * 4 + t) * NIN;
;         sq[i] = bf2f(row[C_MQ + h * 256 + d]) * 0.0625f; sk[i] = bf2f(row[C_MK + h * 256 + d]); sv[i] = bf2f(row[C_MV + h * 256 + d]); }
;     if (tid < 64) sS[tid] = 0.f;
;     __syncthreads();
;     {
;         const int pair = tid >> 5, sub = tid & 31, t = pair >> 2, s = pair & 3; float a = 0.f, c = 0.f;
; #pragma unroll
;         for (int e = 0; e < 8; ++e) { const int d = sub * 8 + e; a += sq[t * 256 + d] * sk[s * 256 + d]; if (s == 0) c += sq[t * 256 + d] * F.in[5][(size_t)bh * 256 + d]; }
; #pragma unroll
;         for (int o = 16; o >= 1; o >>= 1) { a += __shfl_xor(a, o); c += __shfl_xor(c, o); }
;         if (sub == 0) { sS[pair] = a; if (s == 0) sS[16 + t] = c; } }
.LBB0_351:
	s_movk_i32 s35, 0x2c00
	v_mad_i64_i32 v[10:11], s[46:47], v6, s35, v[96:97]
	v_lshl_add_u64 v[12:13], v[10:11], 0, v[0:1]
	v_lshl_add_u64 v[14:15], v[10:11], 0, v[2:3]
	v_lshl_add_u64 v[10:11], v[10:11], 0, v[4:5]
	global_load_ushort v9, v[12:13], off offset:3072
	s_nop 0
	global_load_ushort v12, v[14:15], off
	s_nop 0
	global_load_ushort v10, v[10:11], off
	v_add_co_u32_e32 v8, vcc, 0x200, v8
	s_xor_b64 s[46:47], vcc, -1
	s_and_b64 s[46:47], exec, s[46:47]
	v_add_u32_e32 v6, 2, v6
	s_or_b64 s[42:43], s[46:47], s[42:43]
	s_waitcnt vmcnt(2)
	v_lshlrev_b32_e32 v9, 16, v9
	s_waitcnt vmcnt(1)
	v_lshlrev_b32_e32 v11, 16, v12
	s_waitcnt vmcnt(0)
	v_lshlrev_b32_e32 v10, 16, v10
	v_mul_f32_e32 v9, 0x3d800000, v9
	ds_write_b32 v7, v10 offset:8192
	ds_write2st64_b32 v7, v9, v11 offset1:16
	v_add_u32_e32 v7, 0x800, v7
	s_andn2_b64 exec, exec, s[42:43]
	s_cbranch_execnz .LBB0_351
	s_or_b64 exec, exec, s[42:43]
	s_and_saveexec_b64 s[42:43], s[70:71]
	ds_write_b32 v113, v1 offset:12288
	s_or_b64 exec, exec, s[42:43]
	s_waitcnt lgkmcnt(0)
	s_barrier
	ds_read_b32 v0, v115
	ds_read_b32 v2, v117 offset:4096
	s_ashr_i32 s35, s34, 31
	v_readlane_b32 s12, v245, 37
	s_lshl_b64 s[64:65], s[34:35], 10
	v_readlane_b32 s22, v245, 47
	v_readlane_b32 s23, v245, 48
	s_add_u32 s46, s22, s64
	s_addc_u32 s47, s23, s65
	v_mov_b32_e32 v3, 0
	v_lshlrev_b32_e32 v4, 2, v82
	v_readlane_b32 s13, v245, 38
	v_readlane_b32 s14, v245, 39
	v_readlane_b32 s15, v245, 40
	v_readlane_b32 s16, v245, 41
	v_readlane_b32 s17, v245, 42
	v_readlane_b32 s18, v245, 43
	v_readlane_b32 s19, v245, 44
	v_readlane_b32 s20, v245, 45
	v_readlane_b32 s21, v245, 46
	v_readlane_b32 s24, v245, 49
	v_readlane_b32 s25, v245, 50
	v_readlane_b32 s26, v245, 51
	v_readlane_b32 s27, v245, 52
	s_and_saveexec_b64 s[42:43], s[2:3]
	global_load_dwordx4 v[20:23], v4, s[46:47]
	global_load_dwordx4 v[24:27], v4, s[46:47] offset:16
	s_or_b64 exec, exec, s[42:43]
	ds_read_b32 v5, v115 offset:4
	ds_read_b32 v6, v117 offset:4100
	ds_read_b32 v7, v115 offset:8
	ds_read_b32 v8, v117 offset:4104
	ds_read_b32 v9, v115 offset:12
	ds_read_b32 v10, v117 offset:4108
	ds_read_b32 v11, v115 offset:16
	ds_read_b32 v12, v117 offset:4112
	ds_read_b32 v13, v115 offset:20
	ds_read_b32 v14, v117 offset:4116
	ds_read_b32 v15, v115 offset:24
	ds_read_b32 v16, v117 offset:4120
	ds_read_b32 v17, v115 offset:28
	ds_read_b32 v18, v117 offset:4124
	s_waitcnt lgkmcnt(0)
	s_and_saveexec_b64 s[42:43], s[2:3]
	s_waitcnt vmcnt(0)
	v_fma_f32 v3, v0, v20, 0
	v_fmac_f32_e32 v3, v5, v21
	v_fmac_f32_e32 v3, v7, v22
	v_fmac_f32_e32 v3, v9, v23
	v_fmac_f32_e32 v3, v11, v24
	v_fmac_f32_e32 v3, v13, v25
	v_fmac_f32_e32 v3, v15, v26
	v_fmac_f32_e32 v3, v17, v27
	s_or_b64 exec, exec, s[42:43]
	v_fma_f32 v0, v0, v2, 0
	v_fmac_f32_e32 v0, v5, v6
	v_fmac_f32_e32 v0, v7, v8
	v_fmac_f32_e32 v0, v9, v10
	v_fmac_f32_e32 v0, v11, v12
	v_fmac_f32_e32 v0, v13, v14
	v_fmac_f32_e32 v0, v15, v16
	v_fmac_f32_e32 v0, v17, v18
	ds_bpermute_b32 v2, v83, v3
	ds_bpermute_b32 v4, v83, v0
	s_waitcnt lgkmcnt(1)
	v_add_f32_e32 v2, v3, v2
	s_waitcnt lgkmcnt(0)
	v_add_f32_e32 v0, v0, v4
	ds_bpermute_b32 v3, v101, v2
	ds_bpermute_b32 v4, v101, v0
	s_waitcnt lgkmcnt(1)
	v_add_f32_e32 v2, v2, v3
	s_waitcnt lgkmcnt(0)
	v_add_f32_e32 v0, v0, v4
	ds_bpermute_b32 v3, v105, v2
	ds_bpermute_b32 v4, v105, v0
	s_waitcnt lgkmcnt(1)
	v_add_f32_e32 v2, v2, v3
	s_waitcnt lgkmcnt(0)
	v_add_f32_e32 v4, v0, v4
	ds_bpermute_b32 v3, v107, v2
	ds_bpermute_b32 v5, v107, v4
	s_waitcnt lgkmcnt(1)
	v_add_f32_e32 v0, v2, v3
	s_waitcnt lgkmcnt(0)
	v_add_f32_e32 v3, v4, v5
	ds_bpermute_b32 v4, v109, v3
	ds_bpermute_b32 v2, v109, v0
	s_and_saveexec_b64 s[42:43], s[74:75]
	s_cbranch_execz .LBB0_373
	s_waitcnt lgkmcnt(1)
	v_add_f32_e32 v3, v3, v4
	ds_write_b32 v119, v3 offset:12288
	s_and_b64 exec, exec, s[2:3]
	s_cbranch_execz .LBB0_373
	s_waitcnt lgkmcnt(1)
	v_add_f32_e32 v0, v0, v2
	ds_write_b32 v121, v0 offset:12352

; __device__ __forceinline__ unsigned cvt_pk_bf16(float lo, float hi) { unsigned r; asm volatile("v_cvt_pk_bf16_f32 %0, %1, %2" : "=v"(r) : "v"(lo), "v"(hi)); return r; }
; __device__ __forceinline__ float bf2f(bf16_t h) { return __uint_as_float((unsigned)h << 16); }
; __device__ __forceinline__ float sigmoidf_(float x) { return 1.f / (1.f + __expf(-x)); }
; __device__ __forceinline__ void mlstm_sample_unit(const Frame& F, int b, int h) {
;     ...
; #pragma unroll
;     for (int rg = 0; rg < 4; ++rg)
; #pragma unroll
;         for (int t = 0; t < 4; ++t) if (seg == ((rg * 4 + t) & 7)) { const int vr = w * 32 + rg * 8 + r8; const size_t row = (size_t)(SP + b * 4 + t);
;             const float rms = rsqrtf(sS[32 + t] * (1.f / 256.f) + EPS); const float og = sigmoidf_(bf2f(P[row * NIN + C_MO + h * 256 + vr]));
;             MIX[row * D + 1024 + h * 256 + vr] = (bf16_t)(cvt_pk_bf16(hv[rg][t] * rms * F.in[18][h * 256 + vr] * og, 0.f) & 0xffff); }
.LBB0_396:
	s_or_b64 exec, exec, s[42:43]
	v_readlane_b32 s12, v245, 21
	v_add_u32_e32 v0, s0, v84
	s_lshl_b32 s0, s0, 1
	v_readlane_b32 s16, v245, 25
	v_readlane_b32 s17, v245, 26
	s_waitcnt lgkmcnt(0)
	v_lshl_add_u64 v[2:3], v[92:93], 0, s[0:1]
	s_mul_hi_i32 s28, s62, 0x2c00
	s_mul_i32 s29, s62, 0x2c00
	v_lshlrev_b32_e32 v6, 1, v84
	v_lshl_add_u64 v[4:5], v[0:1], 2, s[16:17]
	s_barrier
	v_readlane_b32 s13, v245, 22
	v_readlane_b32 s14, v245, 23
	v_readlane_b32 s15, v245, 24
	v_readlane_b32 s18, v245, 27
	v_readlane_b32 s19, v245, 28
	v_readlane_b32 s20, v245, 29
	v_readlane_b32 s21, v245, 30
	v_readlane_b32 s22, v245, 31
	v_readlane_b32 s23, v245, 32
	v_readlane_b32 s24, v245, 33
	v_readlane_b32 s25, v245, 34
	v_readlane_b32 s26, v245, 35
	v_readlane_b32 s27, v245, 36
	s_add_u32 s46, s44, s29
	s_addc_u32 s47, s45, s28
	s_add_u32 s46, s46, s0
	s_addc_u32 s47, s47, 0
	s_lshl_b64 s[64:65], s[62:63], 12
	v_and_b32_e32 v45, 3, v144
	v_bfe_u32 v46, v144, 2, 1
	v_mul_u32_u24_e32 v47, 0x2c00, v45
	v_lshl_add_u32 v47, v46, 4, v47
	v_lshlrev_b32_e32 v48, 12, v45
	v_lshl_add_u32 v48, v46, 4, v48
	v_lshlrev_b32_e32 v56, 5, v46
	v_lshlrev_b32_e32 v50, 2, v45
	ds_read_b32 v51, v50 offset:12416
	v_add3_u32 v52, v6, v47, s97
	v_mov_b32_e32 v53, 0
	v_mov_b32_e32 v57, 0
	v_mov_b32_e32 v49, 0
	v_lshl_add_u64 v[52:53], s[46:47], 0, v[52:53]
	v_lshl_add_u64 v[56:57], v[4:5], 0, v[56:57]
	global_load_ushort v54, v[52:53], off offset:1024
	global_load_ushort v55, v[52:53], off offset:1056
	global_load_dword v58, v[56:57], off
	global_load_dword v59, v[56:57], off offset:64
	v_lshl_add_u64 v[60:61], v[2:3], 0, v[48:49]
	v_lshl_add_u64 v[60:61], v[60:61], 0, s[64:65]
	v_mov_b32_e32 v62, v37
	v_cndmask_b32_e64 v62, v62, v38, s[6:7]
	v_cndmask_b32_e64 v62, v62, v41, s[66:67]
	v_cndmask_b32_e64 v62, v62, v44, s[58:59]
	v_cndmask_b32_e64 v62, v62, v43, s[50:51]
	v_cndmask_b32_e64 v62, v62, v42, s[40:41]
	v_cndmask_b32_e64 v62, v62, v40, s[38:39]
	v_cndmask_b32_e64 v62, v62, v39, s[10:11]
	v_mov_b32_e32 v63, v8
	v_cndmask_b32_e64 v63, v63, v10, s[6:7]
	v_cndmask_b32_e64 v63, v63, v11, s[66:67]
	v_cndmask_b32_e64 v63, v63, v14, s[58:59]
	v_cndmask_b32_e64 v63, v63, v26, s[50:51]
	v_cndmask_b32_e64 v63, v63, v34, s[40:41]
	v_cndmask_b32_e64 v63, v63, v35, s[38:39]
	v_cndmask_b32_e64 v63, v63, v36, s[10:11]
	s_waitcnt lgkmcnt(0)
	v_fmamk_f32 v51, v51, 0x3b800000, v131
	v_mul_f32_e32 v64, 0x4b800000, v51
	v_cmp_gt_f32_e32 vcc, s31, v51
	s_nop 1
	v_cndmask_b32_e32 v51, v51, v64, vcc
	v_rsq_f32_e32 v51, v51
	s_nop 0
	v_mul_f32_e32 v64, 0x45800000, v51
	v_cndmask_b32_e32 v51, v51, v64, vcc
	v_mul_f32_e32 v62, v62, v51
	v_mul_f32_e32 v63, v63, v51
	s_waitcnt vmcnt(0)
	v_mul_f32_e32 v62, v58, v62
	v_mul_f32_e32 v63, v59, v63
	v_lshlrev_b32_e32 v54, 16, v54
	v_mul_f32_e32 v54, 0xbfb8aa3b, v54
	v_exp_f32_e32 v54, v54
	s_nop 0
	v_add_f32_e32 v54, 1.0, v54
	v_div_scale_f32 v65, s[42:43], v54, v54, 1.0
	v_rcp_f32_e32 v66, v65
	s_nop 0
	v_fma_f32 v67, -v65, v66, 1.0
	v_fmac_f32_e32 v66, v67, v66
	v_div_scale_f32 v67, vcc, 1.0, v54, 1.0
	v_mul_f32_e32 v68, v67, v66
	v_fma_f32 v69, -v65, v68, v67
	v_fmac_f32_e32 v68, v69, v66
	v_fma_f32 v65, -v65, v68, v67
	v_div_fmas_f32 v65, v65, v66, v68
	v_div_fixup_f32 v54, v65, v54, 1.0
	v_mul_f32_e32 v62, v54, v62
	v_cvt_pk_bf16_f32 v62, v62, v1
	global_store_short v[60:61], v62, off
	v_lshlrev_b32_e32 v55, 16, v55
	v_mul_f32_e32 v55, 0xbfb8aa3b, v55
	v_exp_f32_e32 v55, v55
	s_nop 0
	v_add_f32_e32 v55, 1.0, v55
	v_div_scale_f32 v65, s[42:43], v55, v55, 1.0
	v_rcp_f32_e32 v66, v65
	s_nop 0
	v_fma_f32 v67, -v65, v66, 1.0
	v_fmac_f32_e32 v66, v67, v66
	v_div_scale_f32 v67, vcc, 1.0, v55, 1.0
	v_mul_f32_e32 v68, v67, v66
	v_fma_f32 v69, -v65, v68, v67
	v_fmac_f32_e32 v68, v69, v66
	v_fma_f32 v65, -v65, v68, v67
	v_div_fmas_f32 v65, v65, v66, v68
	v_div_fixup_f32 v55, v65, v55, 1.0
	v_mul_f32_e32 v63, v55, v63
	v_cvt_pk_bf16_f32 v63, v63, v1
	global_store_short v[60:61], v63, off offset:32
	s_branch .LBB0_349

; __device__ __forceinline__ void attn_sample_wave(const Frame& F, int unit) {
;     ...
;     const float* vb = F.in[3] + ((size_t)b * 128 + kq) * 256 + g * 64 + dq * 4;
; #pragma unroll 8
;     for (int kb = 0; kb < 32; ++kb) { const f32x4 vv = *(const f32x4*)(vb + (size_t)kb * 1024);
; #pragma unroll
;         for (int t = 0; t < 4; ++t) o[t] += vv * sp[t * 160 + kb * 4 + kq]; }
.LBB0_525:
	v_lshl_add_u64 v[2:3], v[0:1], 0, s[34:35]
	v_add_co_u32_e32 v90, vcc, 0x2000, v2
	s_nop 1
	v_addc_co_u32_e32 v91, vcc, 0, v3, vcc
	v_add_co_u32_e32 v92, vcc, 0x4000, v2
	s_nop 1
	v_addc_co_u32_e32 v93, vcc, 0, v3, vcc
	v_add_co_u32_e32 v94, vcc, 0x6000, v2
	s_nop 1
	v_addc_co_u32_e32 v95, vcc, 0, v3, vcc
	v_add_co_u32_e32 v96, vcc, 0x7000, v2
	s_nop 1
	v_addc_co_u32_e32 v97, vcc, 0, v3, vcc
	global_load_dwordx4 v[100:103], v[2:3], off
	global_load_dwordx4 v[104:107], v[90:91], off offset:-4096
	global_load_dwordx4 v[108:111], v[90:91], off
	global_load_dwordx4 v[112:115], v[92:93], off offset:-4096
	global_load_dwordx4 v[116:119], v[92:93], off
	global_load_dwordx4 v[120:123], v[94:95], off offset:-4096
	global_load_dwordx4 v[124:127], v[94:95], off
	global_load_dwordx4 v[128:131], v[96:97], off
	v_add_u32_e32 v88, 0x400, v4
	ds_read2_b32 v[162:163], v4 offset1:4
	ds_read2_b32 v[164:165], v4 offset0:8 offset1:12
	ds_read2_b32 v[166:167], v4 offset0:16 offset1:20
	ds_read2_b32 v[168:169], v4 offset0:24 offset1:28
	ds_read2_b32 v[170:171], v4 offset0:160 offset1:164
	ds_read2_b32 v[172:173], v4 offset0:168 offset1:172
	ds_read2_b32 v[174:175], v4 offset0:176 offset1:180
	ds_read2_b32 v[176:177], v4 offset0:184 offset1:188
	ds_read2_b32 v[178:179], v88 offset0:64 offset1:68
	ds_read2_b32 v[180:181], v88 offset0:72 offset1:76
	ds_read2_b32 v[182:183], v88 offset0:80 offset1:84
	ds_read2_b32 v[184:185], v88 offset0:88 offset1:92
	ds_read2_b32 v[186:187], v88 offset0:224 offset1:228
	ds_read2_b32 v[188:189], v88 offset0:232 offset1:236
	ds_read2_b32 v[190:191], v88 offset0:240 offset1:244
	ds_read2_b32 v[192:193], v88 offset0:248 offset1:252
	s_add_u32 s34, s34, 0x8000
	s_addc_u32 s35, s35, 0
	v_add_u32_e32 v4, 0x80, v4
	s_waitcnt lgkmcnt(0)
	s_waitcnt vmcnt(7)
	v_pk_fma_f32 v[34:35], v[100:101], v[162:163], v[34:35] op_sel_hi:[1,0,1]
	v_pk_fma_f32 v[36:37], v[102:103], v[162:163], v[36:37] op_sel_hi:[1,0,1]
	v_pk_fma_f32 v[32:33], v[100:101], v[170:171], v[32:33] op_sel_hi:[1,0,1]
	v_pk_fma_f32 v[30:31], v[102:103], v[170:171], v[30:31] op_sel_hi:[1,0,1]
	v_pk_fma_f32 v[28:29], v[100:101], v[178:179], v[28:29] op_sel_hi:[1,0,1]
	v_pk_fma_f32 v[26:27], v[102:103], v[178:179], v[26:27] op_sel_hi:[1,0,1]
	v_pk_fma_f32 v[24:25], v[100:101], v[186:187], v[24:25] op_sel_hi:[1,0,1]
	v_pk_fma_f32 v[22:23], v[102:103], v[186:187], v[22:23] op_sel_hi:[1,0,1]
	s_waitcnt vmcnt(6)
	v_pk_fma_f32 v[34:35], v[104:105], v[162:163], v[34:35] op_sel:[0,1,0] op_sel_hi:[1,1,1]
	v_pk_fma_f32 v[36:37], v[106:107], v[162:163], v[36:37] op_sel:[0,1,0] op_sel_hi:[1,1,1]
	v_pk_fma_f32 v[32:33], v[104:105], v[170:171], v[32:33] op_sel:[0,1,0] op_sel_hi:[1,1,1]
	v_pk_fma_f32 v[30:31], v[106:107], v[170:171], v[30:31] op_sel:[0,1,0] op_sel_hi:[1,1,1]
	v_pk_fma_f32 v[28:29], v[104:105], v[178:179], v[28:29] op_sel:[0,1,0] op_sel_hi:[1,1,1]
	v_pk_fma_f32 v[26:27], v[106:107], v[178:179], v[26:27] op_sel:[0,1,0] op_sel_hi:[1,1,1]
	v_pk_fma_f32 v[24:25], v[104:105], v[186:187], v[24:25] op_sel:[0,1,0] op_sel_hi:[1,1,1]
	v_pk_fma_f32 v[22:23], v[106:107], v[186:187], v[22:23] op_sel:[0,1,0] op_sel_hi:[1,1,1]
	s_waitcnt vmcnt(5)
	v_pk_fma_f32 v[34:35], v[108:109], v[164:165], v[34:35] op_sel_hi:[1,0,1]
	v_pk_fma_f32 v[36:37], v[110:111], v[164:165], v[36:37] op_sel_hi:[1,0,1]
	v_pk_fma_f32 v[32:33], v[108:109], v[172:173], v[32:33] op_sel_hi:[1,0,1]
	v_pk_fma_f32 v[30:31], v[110:111], v[172:173], v[30:31] op_sel_hi:[1,0,1]
	v_pk_fma_f32 v[28:29], v[108:109], v[180:181], v[28:29] op_sel_hi:[1,0,1]
	v_pk_fma_f32 v[26:27], v[110:111], v[180:181], v[26:27] op_sel_hi:[1,0,1]
	v_pk_fma_f32 v[24:25], v[108:109], v[188:189], v[24:25] op_sel_hi:[1,0,1]
	v_pk_fma_f32 v[22:23], v[110:111], v[188:189], v[22:23] op_sel_hi:[1,0,1]
	s_waitcnt vmcnt(4)
	v_pk_fma_f32 v[34:35], v[112:113], v[164:165], v[34:35] op_sel:[0,1,0] op_sel_hi:[1,1,1]
	v_pk_fma_f32 v[36:37], v[114:115], v[164:165], v[36:37] op_sel:[0,1,0] op_sel_hi:[1,1,1]
	v_pk_fma_f32 v[32:33], v[112:113], v[172:173], v[32:33] op_sel:[0,1,0] op_sel_hi:[1,1,1]
	v_pk_fma_f32 v[30:31], v[114:115], v[172:173], v[30:31] op_sel:[0,1,0] op_sel_hi:[1,1,1]
	v_pk_fma_f32 v[28:29], v[112:113], v[180:181], v[28:29] op_sel:[0,1,0] op_sel_hi:[1,1,1]
	v_pk_fma_f32 v[26:27], v[114:115], v[180:181], v[26:27] op_sel:[0,1,0] op_sel_hi:[1,1,1]
	v_pk_fma_f32 v[24:25], v[112:113], v[188:189], v[24:25] op_sel:[0,1,0] op_sel_hi:[1,1,1]
	v_pk_fma_f32 v[22:23], v[114:115], v[188:189], v[22:23] op_sel:[0,1,0] op_sel_hi:[1,1,1]
	s_waitcnt vmcnt(3)
; #define LAS __attribute__((address_space(3)))
; __device__ __forceinline__ unsigned cvt_pk_bf16(float lo, float hi) { unsigned r; asm volatile("v_cvt_pk_bf16_f32 %0, %1, %2" : "=v"(r) : "v"(lo), "v"(hi)); return r; }
; __device__ __forceinline__ void attn_sample_wave(const Frame& F, int unit) {
;     ...
; #pragma unroll 8
;     for (int kb = 0; kb < 32; ++kb) { const f32x4 vv = *(const f32x4*)(vb + (size_t)kb * 1024);
; #pragma unroll
;         for (int t = 0; t < 4; ++t) o[t] += vv * sp[t * 160 + kb * 4 + kq]; }
;     { const f32x4 vv = *(const LAS f32x4*)(sv + kq * 64 + dq * 4);
; #pragma unroll
;       for (int t = 0; t < 4; ++t) o[t] += vv * sp[t * 160 + 128 + kq]; }
; #pragma unroll
;     for (int t = 0; t < 4; ++t) {
; #pragma unroll
;         for (int e = 0; e < 4; ++e) { float v = o[t][e]; v += __shfl_xor(v, 16); v += __shfl_xor(v, 32); o[t][e] = v * linv[t]; }
;         if (kq == t) { u32x2 pk; pk.x = cvt_pk_bf16(o[t][0], o[t][1]); pk.y = cvt_pk_bf16(o[t][2], o[t][3]); *(u32x2*)(MIX + (size_t)(SP + b * 4 + t) * D + hq * 64 + dq * 4) = pk; } }
	v_pk_fma_f32 v[34:35], v[116:117], v[166:167], v[34:35] op_sel_hi:[1,0,1]
	v_pk_fma_f32 v[36:37], v[118:119], v[166:167], v[36:37] op_sel_hi:[1,0,1]
	v_pk_fma_f32 v[32:33], v[116:117], v[174:175], v[32:33] op_sel_hi:[1,0,1]
	v_pk_fma_f32 v[30:31], v[118:119], v[174:175], v[30:31] op_sel_hi:[1,0,1]
	v_pk_fma_f32 v[28:29], v[116:117], v[182:183], v[28:29] op_sel_hi:[1,0,1]
	v_pk_fma_f32 v[26:27], v[118:119], v[182:183], v[26:27] op_sel_hi:[1,0,1]
	v_pk_fma_f32 v[24:25], v[116:117], v[190:191], v[24:25] op_sel_hi:[1,0,1]
	v_pk_fma_f32 v[22:23], v[118:119], v[190:191], v[22:23] op_sel_hi:[1,0,1]
	s_waitcnt vmcnt(2)
	v_pk_fma_f32 v[34:35], v[120:121], v[166:167], v[34:35] op_sel:[0,1,0] op_sel_hi:[1,1,1]
	v_pk_fma_f32 v[36:37], v[122:123], v[166:167], v[36:37] op_sel:[0,1,0] op_sel_hi:[1,1,1]
	v_pk_fma_f32 v[32:33], v[120:121], v[174:175], v[32:33] op_sel:[0,1,0] op_sel_hi:[1,1,1]
	v_pk_fma_f32 v[30:31], v[122:123], v[174:175], v[30:31] op_sel:[0,1,0] op_sel_hi:[1,1,1]
	v_pk_fma_f32 v[28:29], v[120:121], v[182:183], v[28:29] op_sel:[0,1,0] op_sel_hi:[1,1,1]
	v_pk_fma_f32 v[26:27], v[122:123], v[182:183], v[26:27] op_sel:[0,1,0] op_sel_hi:[1,1,1]
	v_pk_fma_f32 v[24:25], v[120:121], v[190:191], v[24:25] op_sel:[0,1,0] op_sel_hi:[1,1,1]
	v_pk_fma_f32 v[22:23], v[122:123], v[190:191], v[22:23] op_sel:[0,1,0] op_sel_hi:[1,1,1]
	s_waitcnt vmcnt(1)
	v_pk_fma_f32 v[34:35], v[124:125], v[168:169], v[34:35] op_sel_hi:[1,0,1]
	v_pk_fma_f32 v[36:37], v[126:127], v[168:169], v[36:37] op_sel_hi:[1,0,1]
	v_pk_fma_f32 v[32:33], v[124:125], v[176:177], v[32:33] op_sel_hi:[1,0,1]
	v_pk_fma_f32 v[30:31], v[126:127], v[176:177], v[30:31] op_sel_hi:[1,0,1]
	v_pk_fma_f32 v[28:29], v[124:125], v[184:185], v[28:29] op_sel_hi:[1,0,1]
	v_pk_fma_f32 v[26:27], v[126:127], v[184:185], v[26:27] op_sel_hi:[1,0,1]
	v_pk_fma_f32 v[24:25], v[124:125], v[192:193], v[24:25] op_sel_hi:[1,0,1]
	v_pk_fma_f32 v[22:23], v[126:127], v[192:193], v[22:23] op_sel_hi:[1,0,1]
	s_waitcnt vmcnt(0)
	v_pk_fma_f32 v[34:35], v[128:129], v[168:169], v[34:35] op_sel:[0,1,0] op_sel_hi:[1,1,1]
	v_pk_fma_f32 v[36:37], v[130:131], v[168:169], v[36:37] op_sel:[0,1,0] op_sel_hi:[1,1,1]
	v_pk_fma_f32 v[32:33], v[128:129], v[176:177], v[32:33] op_sel:[0,1,0] op_sel_hi:[1,1,1]
	v_pk_fma_f32 v[30:31], v[130:131], v[176:177], v[30:31] op_sel:[0,1,0] op_sel_hi:[1,1,1]
	v_pk_fma_f32 v[28:29], v[128:129], v[184:185], v[28:29] op_sel:[0,1,0] op_sel_hi:[1,1,1]
	v_pk_fma_f32 v[26:27], v[130:131], v[184:185], v[26:27] op_sel:[0,1,0] op_sel_hi:[1,1,1]
	v_pk_fma_f32 v[24:25], v[128:129], v[192:193], v[24:25] op_sel:[0,1,0] op_sel_hi:[1,1,1]
	v_pk_fma_f32 v[22:23], v[130:131], v[192:193], v[22:23] op_sel:[0,1,0] op_sel_hi:[1,1,1]
	s_cmp_eq_u32 s34, 0x20000
	s_cbranch_scc0 .LBB0_525
	v_add_u32_e32 v4, 0xe00, v45
	ds_read_b128 v[0:3], v42 offset:2048
	ds_read2_b32 v[80:81], v4 offset1:160
	v_add_u32_e32 v4, 0x1200, v45
	ds_read2_b32 v[38:39], v4 offset0:64 offset1:224
	s_lshl_b32 s60, s55, 1
	s_waitcnt lgkmcnt(1)
	v_pk_fma_f32 v[34:35], v[0:1], v[80:81], v[34:35] op_sel_hi:[1,0,1]
	v_pk_fma_f32 v[78:79], v[2:3], v[80:81], v[36:37] op_sel_hi:[1,0,1]
	ds_bpermute_b32 v4, v56, v34
	ds_bpermute_b32 v74, v56, v35
	ds_bpermute_b32 v36, v56, v78
	ds_bpermute_b32 v80, v56, v79
	s_waitcnt lgkmcnt(3)
	v_add_f32_e32 v37, v34, v4
	s_waitcnt lgkmcnt(2)
	v_add_f32_e32 v75, v35, v74
	s_waitcnt lgkmcnt(1)
	v_add_f32_e32 v77, v78, v36
	s_waitcnt lgkmcnt(0)
	v_add_f32_e32 v79, v79, v80
	ds_bpermute_b32 v74, v55, v37
	ds_bpermute_b32 v76, v55, v75
	ds_bpermute_b32 v78, v55, v77
	ds_bpermute_b32 v80, v55, v79
	v_mov_b32_e32 v36, v81
	v_mov_b32_e32 v4, v39
	v_lshl_add_u64 v[34:35], v[14:15], 0, s[60:61]
	s_and_saveexec_b64 s[34:35], s[0:1]
	s_cbranch_execz .LBB0_528
	v_sub_f32_e32 v39, v61, v62
	v_mul_f32_e32 v39, 0x3fb8aa3b, v39
	v_exp_f32_e32 v39, v39
	v_add_f32_e32 v62, v63, v64
	s_waitcnt lgkmcnt(0)
	v_add_f32_e32 v64, v79, v80
	v_add_f32_e32 v37, v37, v74
	v_add_f32_e32 v39, v39, v62
	v_div_scale_f32 v62, s[28:29], v39, v39, 1.0
	v_rcp_f32_e32 v63, v62
	v_div_scale_f32 v79, vcc, 1.0, v39, 1.0
	s_lshl_b64 s[28:29], s[96:97], 12
	v_fma_f32 v80, -v62, v63, 1.0
	v_fmac_f32_e32 v63, v80, v63
	v_mul_f32_e32 v80, v79, v63
	v_fma_f32 v81, -v62, v80, v79
	v_fmac_f32_e32 v80, v81, v63
	v_fma_f32 v62, -v62, v80, v79
	v_div_fmas_f32 v62, v62, v63, v80
	v_div_fixup_f32 v39, v62, v39, 1.0
	v_add_f32_e32 v62, v77, v78
	v_mul_f32_e32 v63, v39, v64
	v_mul_f32_e32 v64, v39, v62
	v_add_f32_e32 v62, v75, v76
	v_mul_f32_e32 v62, v39, v62
	v_lshl_add_u64 v[74:75], v[34:35], 0, s[28:29]
	v_mul_f32_e32 v37, v39, v37
	v_cvt_pk_bf16_f32 v62, v37, v62
	v_cvt_pk_bf16_f32 v63, v64, v63
	global_store_dwordx2 v[74:75], v[62:63], off

; __device__ __forceinline__ float bf2f(bf16_t h) { return __uint_as_float((unsigned)h << 16); }
; __device__ __forceinline__ void mlstm_sample_unit(const Frame& F, int b, int h) {
;     ...
;     for (int i = tid; i < 1024; i += 512) { const int t = i >> 8, d = i & 255; const bf16_t* row = P + (size_t)(SP + b * 4 + t) * NIN;
;         sq[i] = bf2f(row[C_MQ + h * 256 + d]) * 0.0625f; sk[i] = bf2f(row[C_MK + h * 256 + d]); sv[i] = bf2f(row[C_MV + h * 256 + d]); }
;     if (tid < 64) sS[tid] = 0.f;
;     __syncthreads();
;     {
;         const int pair = tid >> 5, sub = tid & 31, t = pair >> 2, s = pair & 3; float a = 0.f, c = 0.f;
; #pragma unroll
;         for (int e = 0; e < 8; ++e) { const int d = sub * 8 + e; a += sq[t * 256 + d] * sk[s * 256 + d]; if (s == 0) c += sq[t * 256 + d] * F.in[5][(size_t)bh * 256 + d]; }
; #pragma unroll
;         for (int o = 16; o >= 1; o >>= 1) { a += __shfl_xor(a, o); c += __shfl_xor(c, o); }
;         if (sub == 0) { sS[pair] = a; if (s == 0) sS[16 + t] = c; } }
.LBB0_539:
	s_movk_i32 s35, 0x2c00
	v_mad_i64_i32 v[10:11], s[38:39], v6, s35, v[96:97]
	v_lshl_add_u64 v[12:13], v[10:11], 0, v[0:1]
	v_lshl_add_u64 v[14:15], v[10:11], 0, v[2:3]
	v_lshl_add_u64 v[10:11], v[10:11], 0, v[4:5]
	global_load_ushort v9, v[12:13], off offset:3072
	s_nop 0
	global_load_ushort v12, v[14:15], off
	s_nop 0
	global_load_ushort v10, v[10:11], off
	v_add_co_u32_e32 v8, vcc, 0x200, v8
	s_xor_b64 s[38:39], vcc, -1
	s_and_b64 s[38:39], exec, s[38:39]
	v_add_u32_e32 v6, 2, v6
	s_or_b64 s[0:1], s[38:39], s[0:1]
	s_waitcnt vmcnt(2)
	v_lshlrev_b32_e32 v9, 16, v9
	s_waitcnt vmcnt(1)
	v_lshlrev_b32_e32 v11, 16, v12
	s_waitcnt vmcnt(0)
	v_lshlrev_b32_e32 v10, 16, v10
	v_mul_f32_e32 v9, 0x3d800000, v9
	ds_write_b32 v7, v10 offset:8192
	ds_write2st64_b32 v7, v9, v11 offset1:16
	v_add_u32_e32 v7, 0x800, v7
	s_andn2_b64 exec, exec, s[0:1]
	s_cbranch_execnz .LBB0_539
	s_or_b64 exec, exec, s[0:1]
	s_and_saveexec_b64 s[0:1], s[68:69]
	ds_write_b32 v113, v1 offset:12288
	s_or_b64 exec, exec, s[0:1]
	s_waitcnt lgkmcnt(0)
	s_barrier
	ds_read_b32 v0, v115
	ds_read_b32 v2, v117 offset:4096
	s_ashr_i32 s35, s34, 31
	v_readlane_b32 s12, v245, 37
	s_lshl_b64 s[62:63], s[34:35], 10
	v_readlane_b32 s22, v245, 47
	v_readlane_b32 s23, v245, 48
	s_add_u32 s0, s22, s62
	s_addc_u32 s1, s23, s63
	v_mov_b32_e32 v3, 0
	v_lshlrev_b32_e32 v4, 2, v82
	v_readlane_b32 s13, v245, 38
	v_readlane_b32 s14, v245, 39
	v_readlane_b32 s15, v245, 40
	v_readlane_b32 s16, v245, 41
	v_readlane_b32 s17, v245, 42
	v_readlane_b32 s18, v245, 43
	v_readlane_b32 s19, v245, 44
	v_readlane_b32 s20, v245, 45
	v_readlane_b32 s21, v245, 46
	v_readlane_b32 s24, v245, 49
	v_readlane_b32 s25, v245, 50
	v_readlane_b32 s26, v245, 51
	v_readlane_b32 s27, v245, 52
	s_and_saveexec_b64 s[38:39], s[4:5]
	global_load_dwordx4 v[20:23], v4, s[0:1]
	global_load_dwordx4 v[24:27], v4, s[0:1] offset:16
	s_or_b64 exec, exec, s[38:39]
	ds_read_b32 v5, v115 offset:4
	ds_read_b32 v6, v117 offset:4100
	ds_read_b32 v7, v115 offset:8
	ds_read_b32 v8, v117 offset:4104
	ds_read_b32 v9, v115 offset:12
	ds_read_b32 v10, v117 offset:4108
	ds_read_b32 v11, v115 offset:16
	ds_read_b32 v12, v117 offset:4112
	ds_read_b32 v13, v115 offset:20
	ds_read_b32 v14, v117 offset:4116
	ds_read_b32 v15, v115 offset:24
	ds_read_b32 v16, v117 offset:4120
	ds_read_b32 v17, v115 offset:28
	ds_read_b32 v18, v117 offset:4124
	s_waitcnt lgkmcnt(0)
	s_and_saveexec_b64 s[38:39], s[4:5]
	s_waitcnt vmcnt(0)
	v_fma_f32 v3, v0, v20, 0
	v_fmac_f32_e32 v3, v5, v21
	v_fmac_f32_e32 v3, v7, v22
	v_fmac_f32_e32 v3, v9, v23
	v_fmac_f32_e32 v3, v11, v24
	v_fmac_f32_e32 v3, v13, v25
	v_fmac_f32_e32 v3, v15, v26
	v_fmac_f32_e32 v3, v17, v27
	s_or_b64 exec, exec, s[38:39]
	v_fma_f32 v0, v0, v2, 0
	v_fmac_f32_e32 v0, v5, v6
	v_fmac_f32_e32 v0, v7, v8
	v_fmac_f32_e32 v0, v9, v10
	v_fmac_f32_e32 v0, v11, v12
	v_fmac_f32_e32 v0, v13, v14
	v_fmac_f32_e32 v0, v15, v16
	v_fmac_f32_e32 v0, v17, v18
	ds_bpermute_b32 v2, v83, v3
	ds_bpermute_b32 v4, v83, v0
	s_waitcnt lgkmcnt(1)
	v_add_f32_e32 v2, v3, v2
	s_waitcnt lgkmcnt(0)
	v_add_f32_e32 v0, v0, v4
	ds_bpermute_b32 v3, v99, v2
	ds_bpermute_b32 v4, v99, v0
	s_waitcnt lgkmcnt(1)
	v_add_f32_e32 v2, v2, v3
	s_waitcnt lgkmcnt(0)
	v_add_f32_e32 v0, v0, v4
	ds_bpermute_b32 v3, v105, v2
	ds_bpermute_b32 v4, v105, v0
	s_waitcnt lgkmcnt(1)
	v_add_f32_e32 v2, v2, v3
	s_waitcnt lgkmcnt(0)
	v_add_f32_e32 v4, v0, v4
	ds_bpermute_b32 v3, v107, v2
	ds_bpermute_b32 v5, v107, v4
	s_waitcnt lgkmcnt(1)
	v_add_f32_e32 v0, v2, v3
	s_waitcnt lgkmcnt(0)
	v_add_f32_e32 v3, v4, v5
	ds_bpermute_b32 v4, v109, v3
	ds_bpermute_b32 v2, v109, v0
	s_and_saveexec_b64 s[0:1], s[6:7]
	s_cbranch_execz .LBB0_561
	s_waitcnt lgkmcnt(1)
	v_add_f32_e32 v3, v3, v4
	ds_write_b32 v119, v3 offset:12288
	s_and_b64 exec, exec, s[4:5]
	s_cbranch_execz .LBB0_561
	s_waitcnt lgkmcnt(1)
	v_add_f32_e32 v0, v0, v2
	ds_write_b32 v121, v0 offset:12352

; __device__ __forceinline__ unsigned cvt_pk_bf16(float lo, float hi) { unsigned r; asm volatile("v_cvt_pk_bf16_f32 %0, %1, %2" : "=v"(r) : "v"(lo), "v"(hi)); return r; }
; __device__ __forceinline__ float bf2f(bf16_t h) { return __uint_as_float((unsigned)h << 16); }
; __device__ __forceinline__ float sigmoidf_(float x) { return 1.f / (1.f + __expf(-x)); }
; __device__ __forceinline__ void mlstm_sample_unit(const Frame& F, int b, int h) {
;     ...
; #pragma unroll
;     for (int rg = 0; rg < 4; ++rg)
; #pragma unroll
;         for (int t = 0; t < 4; ++t) if (seg == ((rg * 4 + t) & 7)) { const int vr = w * 32 + rg * 8 + r8; const size_t row = (size_t)(SP + b * 4 + t);
;             const float rms = rsqrtf(sS[32 + t] * (1.f / 256.f) + EPS); const float og = sigmoidf_(bf2f(P[row * NIN + C_MO + h * 256 + vr]));
;             MIX[row * D + 1024 + h * 256 + vr] = (bf16_t)(cvt_pk_bf16(hv[rg][t] * rms * F.in[18][h * 256 + vr] * og, 0.f) & 0xffff); }
.LBB0_584:
	s_or_b64 exec, exec, s[0:1]
	v_readlane_b32 s12, v245, 21
	v_add_u32_e32 v0, s30, v84
	s_lshl_b32 s30, s30, 1
	v_readlane_b32 s16, v245, 25
	v_readlane_b32 s17, v245, 26
	s_waitcnt lgkmcnt(0)
	v_lshl_add_u64 v[2:3], v[92:93], 0, s[30:31]
	s_mul_hi_i32 s43, s54, 0x2c00
	s_mul_i32 s64, s54, 0x2c00
	v_lshlrev_b32_e32 v6, 1, v84
	v_lshl_add_u64 v[4:5], v[0:1], 2, s[16:17]
	s_barrier
	v_readlane_b32 s13, v245, 22
	v_readlane_b32 s14, v245, 23
	v_readlane_b32 s15, v245, 24
	v_readlane_b32 s18, v245, 27
	v_readlane_b32 s19, v245, 28
	v_readlane_b32 s20, v245, 29
	v_readlane_b32 s21, v245, 30
	v_readlane_b32 s22, v245, 31
	v_readlane_b32 s23, v245, 32
	v_readlane_b32 s24, v245, 33
	v_readlane_b32 s25, v245, 34
	v_readlane_b32 s26, v245, 35
	v_readlane_b32 s27, v245, 36
	s_add_u32 s28, s44, s64
	s_addc_u32 s29, s45, s43
	s_add_u32 s28, s28, s30
	s_addc_u32 s29, s29, 0
	s_lshl_b64 s[56:57], s[54:55], 12
	v_and_b32_e32 v45, 3, v144
	v_bfe_u32 v46, v144, 2, 1
	v_mul_u32_u24_e32 v47, 0x2c00, v45
	v_lshl_add_u32 v47, v46, 4, v47
	v_lshlrev_b32_e32 v48, 12, v45
	v_lshl_add_u32 v48, v46, 4, v48
	v_lshlrev_b32_e32 v56, 5, v46
	v_lshlrev_b32_e32 v50, 2, v45
	ds_read_b32 v51, v50 offset:12416
	v_add3_u32 v52, v6, v47, s76
	v_mov_b32_e32 v53, 0
	v_mov_b32_e32 v57, 0
	v_mov_b32_e32 v49, 0
	v_lshl_add_u64 v[52:53], s[28:29], 0, v[52:53]
	v_lshl_add_u64 v[56:57], v[4:5], 0, v[56:57]
	global_load_ushort v54, v[52:53], off offset:1024
	global_load_ushort v55, v[52:53], off offset:1056
	global_load_dword v58, v[56:57], off
	global_load_dword v59, v[56:57], off offset:64
	v_lshl_add_u64 v[60:61], v[2:3], 0, v[48:49]
	v_lshl_add_u64 v[60:61], v[60:61], 0, s[56:57]
	v_mov_b32_e32 v62, v37
	v_cndmask_b32_e64 v62, v62, v38, s[52:53]
	v_cndmask_b32_e64 v62, v62, v39, s[96:97]
	v_cndmask_b32_e64 v62, v62, v40, s[66:67]
	v_cndmask_b32_e64 v62, v62, v41, s[58:59]
	v_cndmask_b32_e64 v62, v62, v42, s[50:51]
	v_cndmask_b32_e64 v62, v62, v44, s[40:41]
	v_cndmask_b32_e64 v62, v62, v43, s[8:9]
	v_mov_b32_e32 v63, v9
	v_cndmask_b32_e64 v63, v63, v8, s[52:53]
	v_cndmask_b32_e64 v63, v63, v10, s[96:97]
	v_cndmask_b32_e64 v63, v63, v14, s[66:67]
	v_cndmask_b32_e64 v63, v63, v26, s[58:59]
	v_cndmask_b32_e64 v63, v63, v34, s[50:51]
	v_cndmask_b32_e64 v63, v63, v35, s[40:41]
	v_cndmask_b32_e64 v63, v63, v36, s[8:9]
	s_waitcnt lgkmcnt(0)
	v_fmamk_f32 v51, v51, 0x3b800000, v131
	v_mul_f32_e32 v64, 0x4b800000, v51
	v_cmp_gt_f32_e32 vcc, s82, v51
	s_nop 1
	v_cndmask_b32_e32 v51, v51, v64, vcc
	v_rsq_f32_e32 v51, v51
	s_nop 0
	v_mul_f32_e32 v64, 0x45800000, v51
	v_cndmask_b32_e32 v51, v51, v64, vcc
	v_mul_f32_e32 v62, v62, v51
	v_mul_f32_e32 v63, v63, v51
	s_waitcnt vmcnt(0)
	v_mul_f32_e32 v62, v58, v62
	v_mul_f32_e32 v63, v59, v63
	v_lshlrev_b32_e32 v54, 16, v54
	v_mul_f32_e32 v54, 0xbfb8aa3b, v54
	v_exp_f32_e32 v54, v54
	s_nop 0
	v_add_f32_e32 v54, 1.0, v54
	v_div_scale_f32 v65, s[0:1], v54, v54, 1.0
	v_rcp_f32_e32 v66, v65
	s_nop 0
	v_fma_f32 v67, -v65, v66, 1.0
	v_fmac_f32_e32 v66, v67, v66
	v_div_scale_f32 v67, vcc, 1.0, v54, 1.0
	v_mul_f32_e32 v68, v67, v66
	v_fma_f32 v69, -v65, v68, v67
	v_fmac_f32_e32 v68, v69, v66
	v_fma_f32 v65, -v65, v68, v67
	v_div_fmas_f32 v65, v65, v66, v68
	v_div_fixup_f32 v54, v65, v54, 1.0
	v_mul_f32_e32 v62, v54, v62
	v_cvt_pk_bf16_f32 v62, v62, v1
	global_store_short v[60:61], v62, off
	v_lshlrev_b32_e32 v55, 16, v55
	v_mul_f32_e32 v55, 0xbfb8aa3b, v55
	v_exp_f32_e32 v55, v55
	s_nop 0
	v_add_f32_e32 v55, 1.0, v55
	v_div_scale_f32 v65, s[0:1], v55, v55, 1.0
	v_rcp_f32_e32 v66, v65
	s_nop 0
	v_fma_f32 v67, -v65, v66, 1.0
	v_fmac_f32_e32 v66, v67, v66
	v_div_scale_f32 v67, vcc, 1.0, v55, 1.0
	v_mul_f32_e32 v68, v67, v66
	v_fma_f32 v69, -v65, v68, v67
	v_fmac_f32_e32 v68, v69, v66
	v_fma_f32 v65, -v65, v68, v67
	v_div_fmas_f32 v65, v65, v66, v68
	v_div_fixup_f32 v55, v65, v55, 1.0
	v_mul_f32_e32 v63, v55, v63
	v_cvt_pk_bf16_f32 v63, v63, v1
	global_store_short v[60:61], v63, off offset:32
	s_branch .LBB0_537
